# v24
# baseline (speedup 1.0000x reference)
.LBB0_209:
	s_cmp_ge_u32 s83, 4
	s_cbranch_scc0 .Lmy_gprio
	s_setprio 1
